# ADIFF fast path: S1 second-half softmax carried into the gaps of the next tile's S0 QK chain; P cvts issued as soon as their last reader has issued (gen_fast5 CARRY=1)
# speedup vs baseline: 1.0335x; 1.0081x over previous
; __device__ __forceinline__ void diff_attn_phase(const Params& p, LAS unsigned char* lds) {
;     ...
;         auto issue = [&](int ch, int stg) {
;             const char* kg = (const char*)(kp + (tokb + 64 * ch) * ld); const char* vg = (const char*)(vp + (tokb + 64 * ch) * ld);
;             LAS unsigned char* sb = lds + stg * STG;
; #pragma unroll
;             for (int i = 0; i < 2; ++i) { unsigned o = doff[i]; asm volatile("" : "+v"(o));
;                 __builtin_amdgcn_global_load_lds((const void*)(kg + o), (LAS void*)(sb + dlds[i]), 16, 0, 0);
;                 __builtin_amdgcn_global_load_lds((const void*)(vg + o), (LAS void*)(sb + 16384 + dlds[i]), 16, 0, 0); }
;         };
;         issue(0, 0); issue(1, 1);
;         int s_cur = 0, s_nn = 2;
;         for (int ch = 0; ch < NCH; ++ch) {
;             if (ch + 1 < NCH) asm volatile("s_waitcnt vmcnt(4)" ::: "memory"); else asm volatile("s_waitcnt vmcnt(0)" ::: "memory");
;             __builtin_amdgcn_s_barrier(); asm volatile("" ::: "memory");
;             if (ch + 2 < NCH) issue(ch + 2, s_nn);
;             const LAS unsigned char* Ksb = lds + s_cur * STG; const LAS unsigned char* Vsb = Ksb + 16384;
;             s_nn = s_cur; s_cur = (s_cur == 2) ? 0 : s_cur + 1;
; #pragma clang loop unroll(disable)
;             for (int u = 0; u < 2; ++u) {
;                 const LAS unsigned char* Ku = Ksb + u * 8192; const LAS unsigned char* Vu = Vsb + u * 8192;
;                 int kxl = kx, vb0l = vb0, vb1l = vb1; asm volatile("" : "+v"(kxl), "+v"(vb0l), "+v"(vb1l));
;                 bf16x8 kf[4];
; #pragma unroll
;                 for (int ks = 0; ks < 4; ++ks) kf[ks] = *(const LAS bf16x8*)(Ku + kbase + (kxl ^ (32 * ks)));
;                 bf16x8 P[2][2];
; #pragma unroll
;                 for (int r = 0; r < 2; ++r) {
;                     f32x16 S;
; #pragma unroll
;                     for (int i = 0; i < 16; ++i) S[i] = 0.f;
; #pragma unroll
;                     for (int ks = 0; ks < 4; ++ks) S = __builtin_amdgcn_mfma_f32_32x32x16_bf16(kf[ks], qf[r][ks], S, 0, 0, 0);
;                     S = __builtin_amdgcn_mfma_f32_32x32x16_bf16(kone, qm[r], S, 0, 0, 0);
; #pragma unroll
;                     for (int i = 0; i < 16; ++i) S[i] = __builtin_amdgcn_exp2f(S[i]);
;                     l[r] += sum16(S);
;                     P[r][0] = pack8(S, 0); P[r][1] = pack8(S, 8);
;                 }
.Lfa_entry:
	s_waitcnt lgkmcnt(0)
	v_readfirstlane_b32 s34, v242
	s_movk_i32 s47, 0x60
	s_waitcnt vmcnt(4)
	s_barrier
	s_add_i32 s2, s29, 2
	s_lshl_b32 s10, s2, 6
	s_add_u32 s10, s26, s10
	s_addc_u32 s11, s27, 0
	s_lshl_b64 s[10:11], s[10:11], 13
	s_add_u32 s42, s25, s10
	s_addc_u32 s43, s28, s11
	s_add_u32 s10, s22, s10
	s_addc_u32 s11, s23, s11
	s_and_b32 s2, s2, 3
	s_lshl_b32 s2, s2, 15
	s_add_i32 s2, s2, s34
	s_mov_b32 m0, s2
	s_add_i32 s35, s2, 0x4000
	global_load_lds_dwordx4 v241, s[42:43]
	s_mov_b32 m0, s35
	s_add_i32 s35, s2, 0x2000
	global_load_lds_dwordx4 v241, s[10:11]
	s_mov_b32 m0, s35
	s_add_i32 s35, s2, 0x6000
	global_load_lds_dwordx4 v243, s[42:43]
	s_mov_b32 m0, s35
	s_nop 0
	global_load_lds_dwordx4 v243, s[10:11]
	v_mov_b32_e32 v1, v245
	v_mov_b32_e32 v234, v247
	v_mov_b32_e32 v235, v248
	v_xor_b32_e32 v237, 64, v247
	v_xor_b32_e32 v236, 64, v248
	v_xor_b32_e32 v238, 0x80, v247
	v_xor_b32_e32 v239, 0x80, v248
	v_xor_b32_e32 v250, 0xc0, v247
	v_xor_b32_e32 v251, 0xc0, v248
	v_add_u32_e32 v198, v246, v1
	ds_read_b128 v[198:201], v198
	v_xad_u32 v202, v246, 32, v1
	ds_read_b128 v[202:205], v202
	v_xad_u32 v208, v246, 64, v1
	ds_read_b128 v[208:211], v208
	v_xad_u32 v230, v246, s47, v1
	ds_read_b128 v[230:233], v230
	s_waitcnt lgkmcnt(3)
	v_mfma_f32_32x32x16_bf16 v[146:161], v[198:201], v[166:169], 0
	v_mfma_f32_32x32x16_bf16 v[130:145], v[198:201], v[182:185], 0
	v_add_u32_e32 v198, v246, v1
	ds_read_b128 v[198:201], v198 offset:8192
	s_waitcnt lgkmcnt(3)
	v_mfma_f32_32x32x16_bf16 v[146:161], v[202:205], v[170:173], v[146:161]
	v_mfma_f32_32x32x16_bf16 v[130:145], v[202:205], v[186:189], v[130:145]
	v_xad_u32 v202, v246, 32, v1
	ds_read_b128 v[202:205], v202 offset:8192
	s_waitcnt lgkmcnt(3)
	v_mfma_f32_32x32x16_bf16 v[146:161], v[208:211], v[174:177], v[146:161]
	v_mfma_f32_32x32x16_bf16 v[130:145], v[208:211], v[190:193], v[130:145]
	v_xad_u32 v208, v246, 64, v1
	ds_read_b128 v[208:211], v208 offset:8192
	s_waitcnt lgkmcnt(3)
	v_mfma_f32_32x32x16_bf16 v[146:161], v[230:233], v[178:181], v[146:161]
	v_mfma_f32_32x32x16_bf16 v[130:145], v[230:233], v[194:197], v[130:145]
	v_xad_u32 v230, v246, s47, v1
	ds_read_b128 v[230:233], v230 offset:8192
	s_nop 7
	s_nop 1
	v_exp_f32_e32 v146, v146
	v_exp_f32_e32 v147, v147
	v_exp_f32_e32 v148, v148
	v_exp_f32_e32 v149, v149
	v_add_f32_e32 v213, v213, v146
	v_add_f32_e32 v213, v213, v147
	v_add_f32_e32 v213, v213, v148
	v_add_f32_e32 v213, v213, v149
	v_exp_f32_e32 v150, v150
	v_exp_f32_e32 v151, v151
	v_exp_f32_e32 v152, v152
	v_exp_f32_e32 v153, v153
	v_add_f32_e32 v213, v213, v150
	v_add_f32_e32 v213, v213, v151
	v_add_f32_e32 v213, v213, v152
	v_add_f32_e32 v213, v213, v153
	v_exp_f32_e32 v154, v154
	v_exp_f32_e32 v155, v155
	v_exp_f32_e32 v156, v156
	v_exp_f32_e32 v157, v157
	v_add_f32_e32 v213, v213, v154
	v_add_f32_e32 v213, v213, v155
	v_add_f32_e32 v213, v213, v156
	v_add_f32_e32 v213, v213, v157
	v_exp_f32_e32 v158, v158
	v_exp_f32_e32 v159, v159
	v_exp_f32_e32 v160, v160
	v_exp_f32_e32 v161, v161
	v_add_f32_e32 v213, v213, v158
	v_add_f32_e32 v213, v213, v159
	v_add_f32_e32 v213, v213, v160
	v_add_f32_e32 v213, v213, v161
	v_exp_f32_e32 v130, v130
	v_exp_f32_e32 v131, v131
	v_exp_f32_e32 v132, v132
	v_exp_f32_e32 v133, v133
	v_add_f32_e32 v212, v212, v130
	v_add_f32_e32 v212, v212, v131
	v_add_f32_e32 v212, v212, v132
	v_add_f32_e32 v212, v212, v133
	v_exp_f32_e32 v134, v134
	v_exp_f32_e32 v135, v135
	v_exp_f32_e32 v136, v136
	v_exp_f32_e32 v137, v137
	v_add_f32_e32 v212, v212, v134
	v_add_f32_e32 v212, v212, v135
	v_add_f32_e32 v212, v212, v136
	v_add_f32_e32 v212, v212, v137
	v_cvt_pk_bf16_f32 v214, v146, v147
	v_cvt_pk_bf16_f32 v215, v148, v149
	v_cvt_pk_bf16_f32 v216, v150, v151
	v_cvt_pk_bf16_f32 v217, v152, v153
	v_cvt_pk_bf16_f32 v218, v130, v131
	v_cvt_pk_bf16_f32 v219, v132, v133
	v_cvt_pk_bf16_f32 v220, v134, v135
	v_cvt_pk_bf16_f32 v221, v136, v137
	v_cvt_pk_bf16_f32 v222, v154, v155
	v_cvt_pk_bf16_f32 v223, v156, v157
	v_cvt_pk_bf16_f32 v224, v158, v159
	v_cvt_pk_bf16_f32 v225, v160, v161
; #define LAS __attribute__((address_space(3)))
; __device__ __forceinline__ void diff_attn_phase(const Params& p, LAS unsigned char* lds) {
;     ...
;                 for (int ks = 0; ks < 4; ++ks) kf[ks] = *(const LAS bf16x8*)(Ku + kbase + (kxl ^ (32 * ks)));
;                 bf16x8 P[2][2];
; #pragma unroll
;                 for (int r = 0; r < 2; ++r) {
;                     f32x16 S;
; #pragma unroll
;                     for (int i = 0; i < 16; ++i) S[i] = 0.f;
; #pragma unroll
;                     for (int ks = 0; ks < 4; ++ks) S = __builtin_amdgcn_mfma_f32_32x32x16_bf16(kf[ks], qf[r][ks], S, 0, 0, 0);
;                     S = __builtin_amdgcn_mfma_f32_32x32x16_bf16(kone, qm[r], S, 0, 0, 0);
; #pragma unroll
;                     for (int i = 0; i < 16; ++i) S[i] = __builtin_amdgcn_exp2f(S[i]);
;                     l[r] += sum16(S);
;                     P[r][0] = pack8(S, 0); P[r][1] = pack8(S, 8);
;                 }
; #pragma unroll
;                 for (int t = 0; t < 4; ++t) {
;                     const LAS unsigned char* a0 = Vu + (vb0l ^ (64 * t)); const LAS unsigned char* a1 = Vu + (vb1l ^ (64 * t));
;                     const bf16x8 v0 = tr_pair(a0, a1), v1 = tr_pair(a0 + 4096, a1 + 4096);
;                     O[0][t] = __builtin_amdgcn_mfma_f32_32x32x16_bf16(v0, P[0][0], O[0][t], 0, 0, 0);
;                     O[1][t] = __builtin_amdgcn_mfma_f32_32x32x16_bf16(v0, P[1][0], O[1][t], 0, 0, 0);
;                     O[0][t] = __builtin_amdgcn_mfma_f32_32x32x16_bf16(v1, P[0][1], O[0][t], 0, 0, 0);
;                     O[1][t] = __builtin_amdgcn_mfma_f32_32x32x16_bf16(v1, P[1][1], O[1][t], 0, 0, 0);
.Lfb_loopF:
	s_waitcnt lgkmcnt(3)
	v_mfma_f32_32x32x16_bf16 v[146:161], v[198:201], v[166:169], 0
	v_exp_f32_e32 v138, v138
	v_exp_f32_e32 v139, v139
	v_exp_f32_e32 v140, v140
	v_exp_f32_e32 v141, v141
	v_add_f32_e32 v212, v212, v138
	s_waitcnt lgkmcnt(2)
	v_mfma_f32_32x32x16_bf16 v[146:161], v[202:205], v[170:173], v[146:161]
	v_add_f32_e32 v212, v212, v139
	v_add_f32_e32 v212, v212, v140
	v_add_f32_e32 v212, v212, v141
	v_exp_f32_e32 v142, v142
	v_exp_f32_e32 v143, v143
	s_waitcnt lgkmcnt(1)
	v_mfma_f32_32x32x16_bf16 v[146:161], v[208:211], v[174:177], v[146:161]
	v_exp_f32_e32 v144, v144
	v_exp_f32_e32 v145, v145
	v_add_f32_e32 v212, v212, v142
	v_add_f32_e32 v212, v212, v143
	v_add_f32_e32 v212, v212, v144
	s_waitcnt lgkmcnt(0)
	v_mfma_f32_32x32x16_bf16 v[146:161], v[230:233], v[178:181], v[146:161]
	v_add_f32_e32 v212, v212, v145
	v_cvt_pk_bf16_f32 v226, v138, v139
	v_cvt_pk_bf16_f32 v227, v140, v141
	v_cvt_pk_bf16_f32 v228, v142, v143
	v_cvt_pk_bf16_f32 v229, v144, v145
	v_mfma_f32_32x32x16_bf16 v[130:145], v[198:201], v[182:185], 0
	ds_read_b64_tr_b16 v[198:199], v234 offset:16384
	ds_read_b64_tr_b16 v[200:201], v235 offset:16384
	v_mfma_f32_32x32x16_bf16 v[130:145], v[202:205], v[186:189], v[130:145]
	ds_read_b64_tr_b16 v[202:203], v237 offset:16384
	ds_read_b64_tr_b16 v[204:205], v236 offset:16384
	v_mfma_f32_32x32x16_bf16 v[130:145], v[208:211], v[190:193], v[130:145]
	ds_read_b64_tr_b16 v[208:209], v238 offset:16384
	ds_read_b64_tr_b16 v[210:211], v239 offset:16384
	v_exp_f32_e32 v146, v146
	v_exp_f32_e32 v147, v147
	v_exp_f32_e32 v148, v148
	v_exp_f32_e32 v149, v149
	v_mfma_f32_32x32x16_bf16 v[130:145], v[230:233], v[194:197], v[130:145]
	ds_read_b64_tr_b16 v[230:231], v250 offset:16384
	ds_read_b64_tr_b16 v[232:233], v251 offset:16384
	v_add_f32_e32 v213, v213, v146
	v_add_f32_e32 v213, v213, v147
	v_add_f32_e32 v213, v213, v148
	v_add_f32_e32 v213, v213, v149
	s_waitcnt lgkmcnt(6)
	v_mfma_f32_32x32x16_bf16 v[114:129], v[198:201], v[214:217], v[114:129]
	v_exp_f32_e32 v150, v150
	v_exp_f32_e32 v151, v151
	v_exp_f32_e32 v152, v152
	v_mfma_f32_32x32x16_bf16 v[50:65], v[198:201], v[218:221], v[50:65]
	ds_read_b64_tr_b16 v[198:199], v234 offset:20480
	ds_read_b64_tr_b16 v[200:201], v235 offset:20480
	v_exp_f32_e32 v153, v153
	v_add_f32_e32 v213, v213, v150
	v_add_f32_e32 v213, v213, v151
	s_waitcnt lgkmcnt(6)
	v_mfma_f32_32x32x16_bf16 v[98:113], v[202:205], v[214:217], v[98:113]
	v_add_f32_e32 v213, v213, v152
	v_add_f32_e32 v213, v213, v153
	v_exp_f32_e32 v154, v154
	v_mfma_f32_32x32x16_bf16 v[34:49], v[202:205], v[218:221], v[34:49]
	ds_read_b64_tr_b16 v[202:203], v237 offset:20480
	ds_read_b64_tr_b16 v[204:205], v236 offset:20480
	v_exp_f32_e32 v155, v155
	v_exp_f32_e32 v156, v156
	v_exp_f32_e32 v157, v157
	s_waitcnt lgkmcnt(6)
	v_mfma_f32_32x32x16_bf16 v[82:97], v[208:211], v[214:217], v[82:97]
	v_add_f32_e32 v213, v213, v154
	v_add_f32_e32 v213, v213, v155
	v_add_f32_e32 v213, v213, v156
	v_mfma_f32_32x32x16_bf16 v[18:33], v[208:211], v[218:221], v[18:33]
	ds_read_b64_tr_b16 v[208:209], v238 offset:20480
	ds_read_b64_tr_b16 v[210:211], v239 offset:20480
	v_add_f32_e32 v213, v213, v157
	v_exp_f32_e32 v158, v158
	v_exp_f32_e32 v159, v159
	s_waitcnt lgkmcnt(6)
	v_mfma_f32_32x32x16_bf16 v[66:81], v[230:233], v[214:217], v[66:81]
	v_exp_f32_e32 v160, v160
	v_exp_f32_e32 v161, v161
	v_add_f32_e32 v213, v213, v158
	v_mfma_f32_32x32x16_bf16 v[2:17], v[230:233], v[218:221], v[2:17]
	ds_read_b64_tr_b16 v[230:231], v250 offset:20480
	ds_read_b64_tr_b16 v[232:233], v251 offset:20480
	v_add_f32_e32 v213, v213, v159
	v_add_f32_e32 v213, v213, v160
	v_add_f32_e32 v213, v213, v161
	s_cmpk_eq_u32 s29, 0x7f
	s_cbranch_scc1 .Lfb_last0F
	s_cmpk_eq_u32 s29, 0x7e
	s_cbranch_scc1 .Lfb_w0F
	s_waitcnt vmcnt(4)
	s_branch .Lfb_w1F

; #define LAS __attribute__((address_space(3)))
; __device__ __forceinline__ void diff_attn_phase(const Params& p, LAS unsigned char* lds) {
;     ...
;                 bf16x8 P[2][2];
; #pragma unroll
;                 for (int r = 0; r < 2; ++r) {
;                     f32x16 S;
; #pragma unroll
;                     for (int i = 0; i < 16; ++i) S[i] = 0.f;
; #pragma unroll
;                     for (int ks = 0; ks < 4; ++ks) S = __builtin_amdgcn_mfma_f32_32x32x16_bf16(kf[ks], qf[r][ks], S, 0, 0, 0);
;                     S = __builtin_amdgcn_mfma_f32_32x32x16_bf16(kone, qm[r], S, 0, 0, 0);
; #pragma unroll
;                     for (int i = 0; i < 16; ++i) S[i] = __builtin_amdgcn_exp2f(S[i]);
;                     l[r] += sum16(S);
;                     P[r][0] = pack8(S, 0); P[r][1] = pack8(S, 8);
;                 }
; #pragma unroll
;                 for (int t = 0; t < 4; ++t) {
;                     const LAS unsigned char* a0 = Vu + (vb0l ^ (64 * t)); const LAS unsigned char* a1 = Vu + (vb1l ^ (64 * t));
;                     const bf16x8 v0 = tr_pair(a0, a1), v1 = tr_pair(a0 + 4096, a1 + 4096);
;                     O[0][t] = __builtin_amdgcn_mfma_f32_32x32x16_bf16(v0, P[0][0], O[0][t], 0, 0, 0);
;                     O[1][t] = __builtin_amdgcn_mfma_f32_32x32x16_bf16(v0, P[1][0], O[1][t], 0, 0, 0);
;                     O[0][t] = __builtin_amdgcn_mfma_f32_32x32x16_bf16(v1, P[0][1], O[0][t], 0, 0, 0);
;                     O[1][t] = __builtin_amdgcn_mfma_f32_32x32x16_bf16(v1, P[1][1], O[1][t], 0, 0, 0);
;                 }
.Lfb_nodmaF:
	s_add_i32 s2, s29, 1
	s_and_b32 s2, s2, 3
	s_mov_b32 s37, 0x8000
	s_cmp_eq_u32 s2, 0
	s_cselect_b32 s37, 0xfffe8000, s37
	v_add_u32_e32 v1, s37, v1
	s_waitcnt lgkmcnt(6)
	v_mfma_f32_32x32x16_bf16 v[114:129], v[198:201], v[222:225], v[114:129]
	v_exp_f32_e32 v130, v130
	v_exp_f32_e32 v131, v131
	v_exp_f32_e32 v132, v132
	v_mfma_f32_32x32x16_bf16 v[50:65], v[198:201], v[226:229], v[50:65]
	v_add_u32_e32 v198, v246, v1
	ds_read_b128 v[198:201], v198
	v_exp_f32_e32 v133, v133
	v_add_f32_e32 v212, v212, v130
	v_add_f32_e32 v212, v212, v131
	s_waitcnt lgkmcnt(5)
	v_mfma_f32_32x32x16_bf16 v[98:113], v[202:205], v[222:225], v[98:113]
	v_add_f32_e32 v212, v212, v132
	v_add_f32_e32 v212, v212, v133
	v_exp_f32_e32 v134, v134
	v_mfma_f32_32x32x16_bf16 v[34:49], v[202:205], v[226:229], v[34:49]
	v_xad_u32 v202, v246, 32, v1
	ds_read_b128 v[202:205], v202
	v_exp_f32_e32 v135, v135
	v_exp_f32_e32 v136, v136
	v_exp_f32_e32 v137, v137
	s_waitcnt lgkmcnt(4)
	v_mfma_f32_32x32x16_bf16 v[82:97], v[208:211], v[222:225], v[82:97]
	v_add_f32_e32 v212, v212, v134
	v_add_f32_e32 v212, v212, v135
	v_add_f32_e32 v212, v212, v136
	v_mfma_f32_32x32x16_bf16 v[18:33], v[208:211], v[226:229], v[18:33]
	v_xad_u32 v208, v246, 64, v1
	ds_read_b128 v[208:211], v208
	v_add_f32_e32 v212, v212, v137
	v_cvt_pk_bf16_f32 v214, v146, v147
	v_cvt_pk_bf16_f32 v215, v148, v149
	s_waitcnt lgkmcnt(3)
	v_mfma_f32_32x32x16_bf16 v[66:81], v[230:233], v[222:225], v[66:81]
	v_cvt_pk_bf16_f32 v216, v150, v151
	v_cvt_pk_bf16_f32 v217, v152, v153
	v_cvt_pk_bf16_f32 v218, v130, v131
	v_cvt_pk_bf16_f32 v219, v132, v133
	v_cvt_pk_bf16_f32 v220, v134, v135
	v_cvt_pk_bf16_f32 v221, v136, v137
	v_cvt_pk_bf16_f32 v222, v154, v155
	v_cvt_pk_bf16_f32 v223, v156, v157
	v_cvt_pk_bf16_f32 v224, v158, v159
	v_cvt_pk_bf16_f32 v225, v160, v161
	v_mfma_f32_32x32x16_bf16 v[2:17], v[230:233], v[226:229], v[2:17]
	v_xad_u32 v230, v246, s47, v1
	ds_read_b128 v[230:233], v230
	s_waitcnt lgkmcnt(3)
	v_mfma_f32_32x32x16_bf16 v[146:161], v[198:201], v[166:169], 0
	v_exp_f32_e32 v138, v138
	v_exp_f32_e32 v139, v139
	v_exp_f32_e32 v140, v140
	v_exp_f32_e32 v141, v141
	v_add_f32_e32 v212, v212, v138
	s_waitcnt lgkmcnt(2)
	v_mfma_f32_32x32x16_bf16 v[146:161], v[202:205], v[170:173], v[146:161]
	v_add_f32_e32 v212, v212, v139
	v_add_f32_e32 v212, v212, v140
	v_add_f32_e32 v212, v212, v141
	v_exp_f32_e32 v142, v142
	v_exp_f32_e32 v143, v143
	s_waitcnt lgkmcnt(1)
	v_mfma_f32_32x32x16_bf16 v[146:161], v[208:211], v[174:177], v[146:161]
	v_exp_f32_e32 v144, v144
	v_exp_f32_e32 v145, v145
	v_add_f32_e32 v212, v212, v142
	v_add_f32_e32 v212, v212, v143
	v_add_f32_e32 v212, v212, v144
	s_waitcnt lgkmcnt(0)
	v_mfma_f32_32x32x16_bf16 v[146:161], v[230:233], v[178:181], v[146:161]
	v_add_f32_e32 v212, v212, v145
	v_cvt_pk_bf16_f32 v226, v138, v139
	v_cvt_pk_bf16_f32 v227, v140, v141
	v_cvt_pk_bf16_f32 v228, v142, v143
	v_cvt_pk_bf16_f32 v229, v144, v145
	v_mfma_f32_32x32x16_bf16 v[130:145], v[198:201], v[182:185], 0
	ds_read_b64_tr_b16 v[198:199], v234 offset:24576
	ds_read_b64_tr_b16 v[200:201], v235 offset:24576
	v_mfma_f32_32x32x16_bf16 v[130:145], v[202:205], v[186:189], v[130:145]
	ds_read_b64_tr_b16 v[202:203], v237 offset:24576
	ds_read_b64_tr_b16 v[204:205], v236 offset:24576
	v_mfma_f32_32x32x16_bf16 v[130:145], v[208:211], v[190:193], v[130:145]
	ds_read_b64_tr_b16 v[208:209], v238 offset:24576
	ds_read_b64_tr_b16 v[210:211], v239 offset:24576
	v_exp_f32_e32 v146, v146
	v_exp_f32_e32 v147, v147
	v_exp_f32_e32 v148, v148
	v_exp_f32_e32 v149, v149
	v_mfma_f32_32x32x16_bf16 v[130:145], v[230:233], v[194:197], v[130:145]
	ds_read_b64_tr_b16 v[230:231], v250 offset:24576
	ds_read_b64_tr_b16 v[232:233], v251 offset:24576
	v_add_f32_e32 v213, v213, v146
	v_add_f32_e32 v213, v213, v147
	v_add_f32_e32 v213, v213, v148
	v_add_f32_e32 v213, v213, v149
	s_waitcnt lgkmcnt(6)
	v_mfma_f32_32x32x16_bf16 v[114:129], v[198:201], v[214:217], v[114:129]
	v_exp_f32_e32 v150, v150
	v_exp_f32_e32 v151, v151
	v_exp_f32_e32 v152, v152
	v_mfma_f32_32x32x16_bf16 v[50:65], v[198:201], v[218:221], v[50:65]
	ds_read_b64_tr_b16 v[198:199], v234 offset:28672
	ds_read_b64_tr_b16 v[200:201], v235 offset:28672
	v_exp_f32_e32 v153, v153
	v_add_f32_e32 v213, v213, v150
	v_add_f32_e32 v213, v213, v151
	s_waitcnt lgkmcnt(6)
	v_mfma_f32_32x32x16_bf16 v[98:113], v[202:205], v[214:217], v[98:113]
	v_add_f32_e32 v213, v213, v152
	v_add_f32_e32 v213, v213, v153
	v_exp_f32_e32 v154, v154
	v_mfma_f32_32x32x16_bf16 v[34:49], v[202:205], v[218:221], v[34:49]
	ds_read_b64_tr_b16 v[202:203], v237 offset:28672
	ds_read_b64_tr_b16 v[204:205], v236 offset:28672
	v_exp_f32_e32 v155, v155
	v_exp_f32_e32 v156, v156
	v_exp_f32_e32 v157, v157
	s_waitcnt lgkmcnt(6)
	v_mfma_f32_32x32x16_bf16 v[82:97], v[208:211], v[214:217], v[82:97]
	v_add_f32_e32 v213, v213, v154
	v_add_f32_e32 v213, v213, v155
	v_add_f32_e32 v213, v213, v156
	v_mfma_f32_32x32x16_bf16 v[18:33], v[208:211], v[218:221], v[18:33]
	ds_read_b64_tr_b16 v[208:209], v238 offset:28672
	ds_read_b64_tr_b16 v[210:211], v239 offset:28672
	v_add_f32_e32 v213, v213, v157
	v_exp_f32_e32 v158, v158
	v_exp_f32_e32 v159, v159
	s_waitcnt lgkmcnt(6)
	v_mfma_f32_32x32x16_bf16 v[66:81], v[230:233], v[214:217], v[66:81]
	v_exp_f32_e32 v160, v160
	v_exp_f32_e32 v161, v161
	v_add_f32_e32 v213, v213, v158
	v_mfma_f32_32x32x16_bf16 v[2:17], v[230:233], v[218:221], v[2:17]
	ds_read_b64_tr_b16 v[230:231], v250 offset:28672
	ds_read_b64_tr_b16 v[232:233], v251 offset:28672
	v_add_f32_e32 v213, v213, v159
	v_add_f32_e32 v213, v213, v160
	v_add_f32_e32 v213, v213, v161
	v_add_u32_e32 v234, s37, v234
	v_add_u32_e32 v235, s37, v235
	v_add_u32_e32 v237, s37, v237
	v_add_u32_e32 v236, s37, v236
	v_add_u32_e32 v238, s37, v238
	v_add_u32_e32 v239, s37, v239
	v_add_u32_e32 v250, s37, v250
	v_add_u32_e32 v251, s37, v251
	s_waitcnt lgkmcnt(6)
; #define LAS __attribute__((address_space(3)))
; __device__ __forceinline__ void diff_attn_phase(const Params& p, LAS unsigned char* lds) {
;     ...
;                 bf16x8 P[2][2];
; #pragma unroll
;                 for (int r = 0; r < 2; ++r) {
;                     f32x16 S;
; #pragma unroll
;                     for (int i = 0; i < 16; ++i) S[i] = 0.f;
; #pragma unroll
;                     for (int ks = 0; ks < 4; ++ks) S = __builtin_amdgcn_mfma_f32_32x32x16_bf16(kf[ks], qf[r][ks], S, 0, 0, 0);
;                     S = __builtin_amdgcn_mfma_f32_32x32x16_bf16(kone, qm[r], S, 0, 0, 0);
; #pragma unroll
;                     for (int i = 0; i < 16; ++i) S[i] = __builtin_amdgcn_exp2f(S[i]);
;                     l[r] += sum16(S);
;                     P[r][0] = pack8(S, 0); P[r][1] = pack8(S, 8);
;                 }
; #pragma unroll
;                 for (int t = 0; t < 4; ++t) {
;                     const LAS unsigned char* a0 = Vu + (vb0l ^ (64 * t)); const LAS unsigned char* a1 = Vu + (vb1l ^ (64 * t));
;                     const bf16x8 v0 = tr_pair(a0, a1), v1 = tr_pair(a0 + 4096, a1 + 4096);
;                     O[0][t] = __builtin_amdgcn_mfma_f32_32x32x16_bf16(v0, P[0][0], O[0][t], 0, 0, 0);
;                     O[1][t] = __builtin_amdgcn_mfma_f32_32x32x16_bf16(v0, P[1][0], O[1][t], 0, 0, 0);
;                     O[0][t] = __builtin_amdgcn_mfma_f32_32x32x16_bf16(v1, P[0][1], O[0][t], 0, 0, 0);
;                     O[1][t] = __builtin_amdgcn_mfma_f32_32x32x16_bf16(v1, P[1][1], O[1][t], 0, 0, 0);
;                 }
	v_mfma_f32_32x32x16_bf16 v[114:129], v[198:201], v[222:225], v[114:129]
	v_exp_f32_e32 v130, v130
	v_exp_f32_e32 v131, v131
	v_exp_f32_e32 v132, v132
	v_mfma_f32_32x32x16_bf16 v[50:65], v[198:201], v[226:229], v[50:65]
	v_add_u32_e32 v198, v246, v1
	ds_read_b128 v[198:201], v198 offset:8192
	v_exp_f32_e32 v133, v133
	v_add_f32_e32 v212, v212, v130
	v_add_f32_e32 v212, v212, v131
	s_waitcnt lgkmcnt(5)
	v_mfma_f32_32x32x16_bf16 v[98:113], v[202:205], v[222:225], v[98:113]
	v_add_f32_e32 v212, v212, v132
	v_add_f32_e32 v212, v212, v133
	v_exp_f32_e32 v134, v134
	v_mfma_f32_32x32x16_bf16 v[34:49], v[202:205], v[226:229], v[34:49]
	v_xad_u32 v202, v246, 32, v1
	ds_read_b128 v[202:205], v202 offset:8192
	v_exp_f32_e32 v135, v135
	v_exp_f32_e32 v136, v136
	v_exp_f32_e32 v137, v137
	s_waitcnt lgkmcnt(4)
	v_mfma_f32_32x32x16_bf16 v[82:97], v[208:211], v[222:225], v[82:97]
	v_add_f32_e32 v212, v212, v134
	v_add_f32_e32 v212, v212, v135
	v_add_f32_e32 v212, v212, v136
	v_mfma_f32_32x32x16_bf16 v[18:33], v[208:211], v[226:229], v[18:33]
	v_xad_u32 v208, v246, 64, v1
	ds_read_b128 v[208:211], v208 offset:8192
	v_add_f32_e32 v212, v212, v137
	v_cvt_pk_bf16_f32 v214, v146, v147
	v_cvt_pk_bf16_f32 v215, v148, v149
	s_waitcnt lgkmcnt(3)
	v_mfma_f32_32x32x16_bf16 v[66:81], v[230:233], v[222:225], v[66:81]
	v_cvt_pk_bf16_f32 v216, v150, v151
	v_cvt_pk_bf16_f32 v217, v152, v153
	v_cvt_pk_bf16_f32 v218, v130, v131
	v_cvt_pk_bf16_f32 v219, v132, v133
	v_cvt_pk_bf16_f32 v220, v134, v135
	v_cvt_pk_bf16_f32 v221, v136, v137
	v_cvt_pk_bf16_f32 v222, v154, v155
	v_cvt_pk_bf16_f32 v223, v156, v157
	v_cvt_pk_bf16_f32 v224, v158, v159
	v_cvt_pk_bf16_f32 v225, v160, v161
	v_mfma_f32_32x32x16_bf16 v[2:17], v[230:233], v[226:229], v[2:17]
	v_xad_u32 v230, v246, s47, v1
	ds_read_b128 v[230:233], v230 offset:8192
	s_add_i32 s29, s29, 1
	s_branch .Lfb_loopF
.Lfb_last0F:
	s_waitcnt lgkmcnt(6)
	v_mfma_f32_32x32x16_bf16 v[114:129], v[198:201], v[222:225], v[114:129]
	v_exp_f32_e32 v130, v130
	v_exp_f32_e32 v131, v131
	v_exp_f32_e32 v132, v132
	v_mfma_f32_32x32x16_bf16 v[50:65], v[198:201], v[226:229], v[50:65]
	ds_read_b64_tr_b16 v[198:199], v234 offset:24576
	ds_read_b64_tr_b16 v[200:201], v235 offset:24576
	v_exp_f32_e32 v133, v133
	v_add_f32_e32 v212, v212, v130
	v_add_f32_e32 v212, v212, v131
	s_waitcnt lgkmcnt(6)
	v_mfma_f32_32x32x16_bf16 v[98:113], v[202:205], v[222:225], v[98:113]
	v_add_f32_e32 v212, v212, v132
	v_add_f32_e32 v212, v212, v133
	v_exp_f32_e32 v134, v134
	v_mfma_f32_32x32x16_bf16 v[34:49], v[202:205], v[226:229], v[34:49]
	ds_read_b64_tr_b16 v[202:203], v237 offset:24576
	ds_read_b64_tr_b16 v[204:205], v236 offset:24576
	v_exp_f32_e32 v135, v135
	v_exp_f32_e32 v136, v136
	v_exp_f32_e32 v137, v137
	s_waitcnt lgkmcnt(6)
	v_mfma_f32_32x32x16_bf16 v[82:97], v[208:211], v[222:225], v[82:97]
	v_add_f32_e32 v212, v212, v134
	v_add_f32_e32 v212, v212, v135
	v_add_f32_e32 v212, v212, v136
	v_mfma_f32_32x32x16_bf16 v[18:33], v[208:211], v[226:229], v[18:33]
	ds_read_b64_tr_b16 v[208:209], v238 offset:24576
	ds_read_b64_tr_b16 v[210:211], v239 offset:24576
	v_add_f32_e32 v212, v212, v137
	v_cvt_pk_bf16_f32 v214, v146, v147
	v_cvt_pk_bf16_f32 v215, v148, v149
	s_waitcnt lgkmcnt(6)
	v_mfma_f32_32x32x16_bf16 v[66:81], v[230:233], v[222:225], v[66:81]
	v_cvt_pk_bf16_f32 v216, v150, v151
	v_cvt_pk_bf16_f32 v217, v152, v153
	v_cvt_pk_bf16_f32 v218, v130, v131
	v_cvt_pk_bf16_f32 v219, v132, v133
	v_cvt_pk_bf16_f32 v220, v134, v135
	v_cvt_pk_bf16_f32 v221, v136, v137
	v_cvt_pk_bf16_f32 v222, v154, v155
	v_cvt_pk_bf16_f32 v223, v156, v157
	v_cvt_pk_bf16_f32 v224, v158, v159
	v_cvt_pk_bf16_f32 v225, v160, v161
	v_mfma_f32_32x32x16_bf16 v[2:17], v[230:233], v[226:229], v[2:17]
	ds_read_b64_tr_b16 v[230:231], v250 offset:24576
	ds_read_b64_tr_b16 v[232:233], v251 offset:24576
	v_exp_f32_e32 v138, v138
	v_exp_f32_e32 v139, v139
	v_exp_f32_e32 v140, v140
	v_exp_f32_e32 v141, v141
	v_add_f32_e32 v212, v212, v138
	v_add_f32_e32 v212, v212, v139
	v_add_f32_e32 v212, v212, v140
	v_add_f32_e32 v212, v212, v141
	v_exp_f32_e32 v142, v142
	v_exp_f32_e32 v143, v143
	v_exp_f32_e32 v144, v144
	v_exp_f32_e32 v145, v145
	v_add_f32_e32 v212, v212, v142
	v_add_f32_e32 v212, v212, v143
	v_add_f32_e32 v212, v212, v144
	v_add_f32_e32 v212, v212, v145
	v_cvt_pk_bf16_f32 v226, v138, v139
	v_cvt_pk_bf16_f32 v227, v140, v141
	v_cvt_pk_bf16_f32 v228, v142, v143
	v_cvt_pk_bf16_f32 v229, v144, v145
	s_waitcnt lgkmcnt(6)
	v_mfma_f32_32x32x16_bf16 v[114:129], v[198:201], v[214:217], v[114:129]
	v_mfma_f32_32x32x16_bf16 v[50:65], v[198:201], v[218:221], v[50:65]
	ds_read_b64_tr_b16 v[198:199], v234 offset:28672
	ds_read_b64_tr_b16 v[200:201], v235 offset:28672
	s_waitcnt lgkmcnt(6)
	v_mfma_f32_32x32x16_bf16 v[98:113], v[202:205], v[214:217], v[98:113]
	v_mfma_f32_32x32x16_bf16 v[34:49], v[202:205], v[218:221], v[34:49]
	ds_read_b64_tr_b16 v[202:203], v237 offset:28672
	ds_read_b64_tr_b16 v[204:205], v236 offset:28672
	s_waitcnt lgkmcnt(6)
	v_mfma_f32_32x32x16_bf16 v[82:97], v[208:211], v[214:217], v[82:97]
	v_mfma_f32_32x32x16_bf16 v[18:33], v[208:211], v[218:221], v[18:33]
	ds_read_b64_tr_b16 v[208:209], v238 offset:28672
	ds_read_b64_tr_b16 v[210:211], v239 offset:28672
	s_waitcnt lgkmcnt(6)
	v_mfma_f32_32x32x16_bf16 v[66:81], v[230:233], v[214:217], v[66:81]
	v_mfma_f32_32x32x16_bf16 v[2:17], v[230:233], v[218:221], v[2:17]
	ds_read_b64_tr_b16 v[230:231], v250 offset:28672
	ds_read_b64_tr_b16 v[232:233], v251 offset:28672
	s_waitcnt lgkmcnt(6)
	v_mfma_f32_32x32x16_bf16 v[114:129], v[198:201], v[222:225], v[114:129]
	v_mfma_f32_32x32x16_bf16 v[50:65], v[198:201], v[226:229], v[50:65]
	s_waitcnt lgkmcnt(4)
	v_mfma_f32_32x32x16_bf16 v[98:113], v[202:205], v[222:225], v[98:113]
	v_mfma_f32_32x32x16_bf16 v[34:49], v[202:205], v[226:229], v[34:49]
	s_waitcnt lgkmcnt(2)
	v_mfma_f32_32x32x16_bf16 v[82:97], v[208:211], v[222:225], v[82:97]
	v_mfma_f32_32x32x16_bf16 v[18:33], v[208:211], v[226:229], v[18:33]
	s_waitcnt lgkmcnt(0)
	v_mfma_f32_32x32x16_bf16 v[66:81], v[230:233], v[222:225], v[66:81]
	v_mfma_f32_32x32x16_bf16 v[2:17], v[230:233], v[226:229], v[2:17]
	s_branch .Lad_epi
